# LRU chunk loop: prefetch of interior chunks without bounds masks or zero fill, tap addresses chained from one base
# baseline (speedup 1.0000x reference)
.LBB0_321:
	s_andn2_b64 vcc, exec, s[46:47]
	s_cbranch_vccnz .LBB0_337
	s_cmp_lt_u32 s15, 12
	s_cbranch_scc0 .Llru_slow
	s_mov_b32 s98, 0x1000
	s_mov_b32 s99, 0
	v_add_u32_e32 v0, 0x180, v123
	v_add_u32_e32 v1, 0x67f, v151
	v_cndmask_b32_e64 v33, v1, v0, s[12:13]
	v_add_u32_e32 v33, -1, v33
	v_mul_u32_u24_e32 v0, s60, v33
	v_mov_b32_e32 v1, v32
	v_lshl_add_u64 v[0:1], v[0:1], 1, v[164:165]
	global_load_dwordx4 v[76:79], v[0:1], off offset:1536
	v_lshl_add_u64 v[0:1], v[0:1], 0, s[40:41]
	global_load_dwordx4 v[80:83], v[0:1], off offset:3584
	v_lshl_add_u64 v[0:1], v[0:1], 0, s[98:99]
	global_load_dwordx4 v[72:75], v[0:1], off offset:3072
	v_lshl_add_u64 v[0:1], v[0:1], 0, s[98:99]
	global_load_dwordx4 v[84:87], v[0:1], off offset:2560
	v_add_u32_e32 v0, 0x1c0, v123
	v_add_u32_e32 v1, 0x63f, v151
	v_cndmask_b32_e64 v33, v1, v0, s[12:13]
	v_add_u32_e32 v33, -1, v33
	v_mul_u32_u24_e32 v34, s60, v33
	v_mov_b32_e32 v35, v32
	v_lshl_add_u64 v[34:35], v[34:35], 1, v[164:165]
	global_load_dwordx4 v[88:91], v[34:35], off offset:1536
	v_lshl_add_u64 v[34:35], v[34:35], 0, s[40:41]
	global_load_dwordx4 v[92:95], v[34:35], off offset:3584
	v_lshl_add_u64 v[34:35], v[34:35], 0, s[98:99]
	global_load_dwordx4 v[96:99], v[34:35], off offset:3072
	v_lshl_add_u64 v[34:35], v[34:35], 0, s[98:99]
	global_load_dwordx4 v[100:103], v[34:35], off offset:2560
	s_branch .Llru_join
.Llru_slow:
	v_add_u32_e32 v0, 0x180, v123
	v_add_u32_e32 v1, 0x67f, v151
	v_cndmask_b32_e64 v33, v1, v0, s[12:13]
	v_mov_b32_e32 v74, v32
	v_mov_b32_e32 v75, v32
	v_add_u32_e32 v0, -1, v33
	v_mov_b32_e32 v72, v32
	v_mov_b32_e32 v73, v32
	v_mov_b64_e32 v[78:79], v[74:75]
	v_cmp_gt_u32_e32 vcc, s50, v0
	v_mov_b64_e32 v[76:77], v[72:73]
	s_and_saveexec_b64 s[46:47], vcc
	s_cbranch_execz .LBB0_324
	v_mul_u32_u24_e32 v0, s60, v0
	v_mov_b32_e32 v1, v32
	v_lshl_add_u64 v[0:1], v[0:1], 1, v[164:165]
	global_load_dwordx4 v[76:79], v[0:1], off offset:1536
